# v18 + GEMM unit loops of P4/P5/P6/P7 start without the conservative vmcnt(0) (K-loop counted waits cover the LDS-DMA)
# speedup vs baseline: 1.0127x; 1.0127x over previous
; template <class Epi, class Sched, bool ALIGN_EPI = false, bool SP2 = false, bool AGM = false  >
; __device__ __forceinline__ void gemm_phase(PG8_LAS unsigned char* lds, const Gemm g, const Sched& S, const Epi& E) {
;     ...
;     Unit cur, nxt; int ui = 0;
;     if (!S.next(0, cur)) return;
;     f32x4 acc[2][2][4][2];
; #pragma unroll
;     for (int a = 0; a < 2; ++a)
; #pragma unroll
;         for (int b = 0; b < 2; ++b)
; #pragma unroll
;             for (int m = 0; m < 4; ++m)
; #pragma unroll
;                 for (int n = 0; n < 2; ++n) acc[a][b][m][n] = (f32x4){0.f, 0.f, 0.f, 0.f};
;     ...
;         const bool has_next = S.next(ui + 1, nxt);
;         const char* nA = has_next ? (const char*)g.A + (size_t)nxt.pm * tstepA : cA; const char* nB = has_next ? (const char*)g.Bt + (size_t)nxt.pn * tstep : cB;
.LBB0_676:
	s_ashr_i32 s19, s18, 31
	s_lshl_b64 s[20:21], s[18:19], 13
	s_add_u32 s20, s64, s20
	s_addc_u32 s21, s65, s21
	s_and_b64 s[22:23], s[0:1], exec
	s_cselect_b32 s19, s21, s25
	s_cselect_b32 s62, s20, s24
	s_ashr_i32 s17, s16, 31
	s_lshl_b64 s[22:23], s[16:17], 18
	s_add_u32 s22, s3, s22
	s_addc_u32 s23, s36, s23
	s_and_b64 s[28:29], s[0:1], exec
	s_cselect_b32 s17, s23, s27
	s_cselect_b32 s63, s22, s26
	s_add_u32 s68, s26, 0x100
	v_mov_b32_e32 v2, 0
	s_addc_u32 s69, s27, 0
	s_mov_b32 s70, -2
	v_mov_b32_e32 v3, v2
	v_mov_b32_e32 v4, v2
	v_mov_b32_e32 v5, v2
	v_mov_b32_e32 v6, v2
	v_mov_b32_e32 v7, v2
	v_mov_b32_e32 v8, v2
	v_mov_b32_e32 v9, v2
	v_mov_b32_e32 v18, v2
	v_mov_b32_e32 v19, v2
	v_mov_b32_e32 v20, v2
	v_mov_b32_e32 v21, v2
	v_mov_b32_e32 v22, v2
	v_mov_b32_e32 v23, v2
	v_mov_b32_e32 v24, v2
	v_mov_b32_e32 v25, v2
	v_mov_b32_e32 v34, v2
	v_mov_b32_e32 v35, v2
	v_mov_b32_e32 v36, v2
	v_mov_b32_e32 v37, v2
	v_mov_b32_e32 v38, v2
	v_mov_b32_e32 v39, v2
	v_mov_b32_e32 v40, v2
	v_mov_b32_e32 v41, v2
	v_mov_b32_e32 v50, v2
	v_mov_b32_e32 v51, v2
	v_mov_b32_e32 v52, v2
	v_mov_b32_e32 v53, v2
	v_mov_b32_e32 v54, v2
	v_mov_b32_e32 v55, v2
	v_mov_b32_e32 v56, v2
	v_mov_b32_e32 v57, v2
	v_mov_b32_e32 v10, v2
	v_mov_b32_e32 v11, v2
	v_mov_b32_e32 v12, v2
	v_mov_b32_e32 v13, v2
	v_mov_b32_e32 v14, v2
	v_mov_b32_e32 v15, v2
	v_mov_b32_e32 v16, v2
	v_mov_b32_e32 v17, v2
	v_mov_b32_e32 v26, v2
	v_mov_b32_e32 v27, v2
	v_mov_b32_e32 v28, v2
	v_mov_b32_e32 v29, v2
	v_mov_b32_e32 v30, v2
	v_mov_b32_e32 v31, v2
	v_mov_b32_e32 v32, v2
	v_mov_b32_e32 v33, v2
	v_mov_b32_e32 v42, v2
	v_mov_b32_e32 v43, v2
	v_mov_b32_e32 v44, v2
	v_mov_b32_e32 v45, v2
	v_mov_b32_e32 v46, v2
	v_mov_b32_e32 v47, v2
	v_mov_b32_e32 v48, v2
	v_mov_b32_e32 v49, v2
	v_mov_b32_e32 v58, v2
	v_mov_b32_e32 v59, v2
	v_mov_b32_e32 v60, v2
	v_mov_b32_e32 v61, v2
	v_mov_b32_e32 v62, v2
	v_mov_b32_e32 v63, v2
	v_mov_b32_e32 v64, v2
	v_mov_b32_e32 v65, v2
	v_mov_b32_e32 v66, v2
	v_mov_b32_e32 v67, v2
	v_mov_b32_e32 v68, v2
	v_mov_b32_e32 v69, v2
	v_mov_b32_e32 v70, v2
	v_mov_b32_e32 v71, v2
	v_mov_b32_e32 v72, v2
	v_mov_b32_e32 v73, v2
	v_mov_b32_e32 v82, v2
	v_mov_b32_e32 v83, v2
	v_mov_b32_e32 v84, v2
	v_mov_b32_e32 v85, v2
	v_mov_b32_e32 v86, v2
	v_mov_b32_e32 v87, v2
	v_mov_b32_e32 v88, v2
	v_mov_b32_e32 v89, v2
	v_mov_b32_e32 v98, v2
	v_mov_b32_e32 v99, v2
	v_mov_b32_e32 v100, v2
	v_mov_b32_e32 v101, v2
	v_mov_b32_e32 v102, v2
	v_mov_b32_e32 v103, v2
	v_mov_b32_e32 v104, v2
	v_mov_b32_e32 v105, v2
	v_mov_b32_e32 v114, v2
	v_mov_b32_e32 v115, v2
	v_mov_b32_e32 v116, v2
	v_mov_b32_e32 v117, v2
	v_mov_b32_e32 v118, v2
	v_mov_b32_e32 v119, v2
	v_mov_b32_e32 v120, v2
	v_mov_b32_e32 v121, v2
	v_mov_b32_e32 v74, v2
	v_mov_b32_e32 v75, v2
	v_mov_b32_e32 v76, v2
	v_mov_b32_e32 v77, v2
	v_mov_b32_e32 v78, v2
	v_mov_b32_e32 v79, v2
	v_mov_b32_e32 v80, v2
	v_mov_b32_e32 v81, v2
	v_mov_b32_e32 v90, v2
	v_mov_b32_e32 v91, v2
	v_mov_b32_e32 v92, v2
	v_mov_b32_e32 v93, v2
	v_mov_b32_e32 v94, v2
	v_mov_b32_e32 v95, v2
	v_mov_b32_e32 v96, v2
	v_mov_b32_e32 v97, v2
	v_mov_b32_e32 v106, v2
	v_mov_b32_e32 v107, v2
	v_mov_b32_e32 v108, v2
	v_mov_b32_e32 v109, v2
	v_mov_b32_e32 v110, v2
	v_mov_b32_e32 v111, v2
	v_mov_b32_e32 v112, v2
	v_mov_b32_e32 v113, v2
	v_mov_b32_e32 v122, v2
	v_mov_b32_e32 v123, v2
	v_mov_b32_e32 v124, v2
	v_mov_b32_e32 v125, v2
	v_mov_b32_e32 v126, v2
	v_mov_b32_e32 v127, v2
	v_mov_b32_e32 v128, v2
	v_mov_b32_e32 v129, v2

; template <class Epi, class Sched, bool ALIGN_EPI = false, bool SP2 = false, bool AGM = false  >
; __device__ __forceinline__ void gemm_phase(PG8_LAS unsigned char* lds, const Gemm g, const Sched& S, const Epi& E) {
;     ...
;     Unit cur, nxt; int ui = 0;
;     if (!S.next(0, cur)) return;
;     f32x4 acc[2][2][4][2];
; #pragma unroll
;     for (int a = 0; a < 2; ++a)
; #pragma unroll
;         for (int b = 0; b < 2; ++b)
; #pragma unroll
;             for (int m = 0; m < 4; ++m)
; #pragma unroll
;                 for (int n = 0; n < 2; ++n) acc[a][b][m][n] = (f32x4){0.f, 0.f, 0.f, 0.f};
;     ...
;         const bool has_next = S.next(ui + 1, nxt);
;         const char* nA = has_next ? (const char*)g.A + (size_t)nxt.pm * tstepA : cA; const char* nB = has_next ? (const char*)g.Bt + (size_t)nxt.pn * tstep : cB;
.LBB0_782:
	s_ashr_i32 s31, s30, 31
	s_lshl_b64 s[34:35], s[30:31], 19
	s_add_u32 s34, s8, s34
	s_addc_u32 s35, s9, s35
	s_and_b64 s[36:37], s[6:7], exec
	s_cselect_b32 s5, s35, s39
	s_cselect_b32 s31, s34, s38
	s_ashr_i32 s29, s28, 31
	s_lshl_b64 s[36:37], s[28:29], 19
	s_add_u32 s36, s14, s36
	s_addc_u32 s37, s15, s37
	s_and_b64 s[42:43], s[6:7], exec
	s_cselect_b32 s29, s37, s41
	s_cselect_b32 s33, s36, s40
	s_add_u32 s38, s38, 0x40080
	s_addc_u32 s39, s39, 0
	s_add_u32 s62, s40, 0x100
	v_mov_b32_e32 v2, 0
	s_addc_u32 s74, s41, 0
	s_mov_b32 s75, -2
	v_mov_b32_e32 v3, v2
	s_waitcnt lgkmcnt(0)
	v_mov_b32_e32 v4, v2
	v_mov_b32_e32 v5, v2
	v_mov_b32_e32 v6, v2
	v_mov_b32_e32 v7, v2
	v_mov_b32_e32 v8, v2
	v_mov_b32_e32 v9, v2
	v_mov_b32_e32 v18, v2
	v_mov_b32_e32 v19, v2
	v_mov_b32_e32 v20, v2
	v_mov_b32_e32 v21, v2
	v_mov_b32_e32 v22, v2
	v_mov_b32_e32 v23, v2
	v_mov_b32_e32 v24, v2
	v_mov_b32_e32 v25, v2
	v_mov_b32_e32 v34, v2
	v_mov_b32_e32 v35, v2
	v_mov_b32_e32 v36, v2
	v_mov_b32_e32 v37, v2
	v_mov_b32_e32 v38, v2
	v_mov_b32_e32 v39, v2
	v_mov_b32_e32 v40, v2
	v_mov_b32_e32 v41, v2
	v_mov_b32_e32 v50, v2
	v_mov_b32_e32 v51, v2
	v_mov_b32_e32 v52, v2
	v_mov_b32_e32 v53, v2
	v_mov_b32_e32 v54, v2
	v_mov_b32_e32 v55, v2
	v_mov_b32_e32 v56, v2
	v_mov_b32_e32 v57, v2
	v_mov_b32_e32 v10, v2
	v_mov_b32_e32 v11, v2
	v_mov_b32_e32 v12, v2
	v_mov_b32_e32 v13, v2
	v_mov_b32_e32 v14, v2
	v_mov_b32_e32 v15, v2
	v_mov_b32_e32 v16, v2
	v_mov_b32_e32 v17, v2
	v_mov_b32_e32 v26, v2
	v_mov_b32_e32 v27, v2
	v_mov_b32_e32 v28, v2
	v_mov_b32_e32 v29, v2
	v_mov_b32_e32 v30, v2
	v_mov_b32_e32 v31, v2
	v_mov_b32_e32 v32, v2
	v_mov_b32_e32 v33, v2
	v_mov_b32_e32 v42, v2
	v_mov_b32_e32 v43, v2
	v_mov_b32_e32 v44, v2
	v_mov_b32_e32 v45, v2
	v_mov_b32_e32 v46, v2
	v_mov_b32_e32 v47, v2
	v_mov_b32_e32 v48, v2
	v_mov_b32_e32 v49, v2
	v_mov_b32_e32 v58, v2
	v_mov_b32_e32 v59, v2
	v_mov_b32_e32 v60, v2
	v_mov_b32_e32 v61, v2
	v_mov_b32_e32 v62, v2
	v_mov_b32_e32 v63, v2
	v_mov_b32_e32 v64, v2
	v_mov_b32_e32 v65, v2
	v_mov_b32_e32 v66, v2
	v_mov_b32_e32 v67, v2
	v_mov_b32_e32 v68, v2
	v_mov_b32_e32 v69, v2
	v_mov_b32_e32 v70, v2
	v_mov_b32_e32 v71, v2
	v_mov_b32_e32 v72, v2
	v_mov_b32_e32 v73, v2
	v_mov_b32_e32 v82, v2
	v_mov_b32_e32 v83, v2
	v_mov_b32_e32 v84, v2
	v_mov_b32_e32 v85, v2
	v_mov_b32_e32 v86, v2
	v_mov_b32_e32 v87, v2
	v_mov_b32_e32 v88, v2
	v_mov_b32_e32 v89, v2
	v_mov_b32_e32 v98, v2
	v_mov_b32_e32 v99, v2
	v_mov_b32_e32 v100, v2
	v_mov_b32_e32 v101, v2
	v_mov_b32_e32 v102, v2
	v_mov_b32_e32 v103, v2
	v_mov_b32_e32 v104, v2
	v_mov_b32_e32 v105, v2
	v_mov_b32_e32 v114, v2
	v_mov_b32_e32 v115, v2
	v_mov_b32_e32 v116, v2
	v_mov_b32_e32 v117, v2
	v_mov_b32_e32 v118, v2
	v_mov_b32_e32 v119, v2
	v_mov_b32_e32 v120, v2
	v_mov_b32_e32 v121, v2
	v_mov_b32_e32 v74, v2
	v_mov_b32_e32 v75, v2
	v_mov_b32_e32 v76, v2
	v_mov_b32_e32 v77, v2
	v_mov_b32_e32 v78, v2
	v_mov_b32_e32 v79, v2
	v_mov_b32_e32 v80, v2
	v_mov_b32_e32 v81, v2
	v_mov_b32_e32 v90, v2
	v_mov_b32_e32 v91, v2
	v_mov_b32_e32 v92, v2
	v_mov_b32_e32 v93, v2
	v_mov_b32_e32 v94, v2
	v_mov_b32_e32 v95, v2
	v_mov_b32_e32 v96, v2
	v_mov_b32_e32 v97, v2
	v_mov_b32_e32 v106, v2
	v_mov_b32_e32 v107, v2
	v_mov_b32_e32 v108, v2
	v_mov_b32_e32 v109, v2
	v_mov_b32_e32 v110, v2
	v_mov_b32_e32 v111, v2
	v_mov_b32_e32 v112, v2
	v_mov_b32_e32 v113, v2
	v_mov_b32_e32 v122, v2
	v_mov_b32_e32 v123, v2
	v_mov_b32_e32 v124, v2
	v_mov_b32_e32 v125, v2
	v_mov_b32_e32 v126, v2
	v_mov_b32_e32 v127, v2
	v_mov_b32_e32 v128, v2
	v_mov_b32_e32 v129, v2

; #define PG8_STAGE(bufoff, gbase, voff) do { _Pragma("unroll") for (int _i = 0; _i < 2; ++_i) \
;         __builtin_amdgcn_global_load_lds((const unsigned*)((const char*)(gbase) + (voff)[_i]), (PG8_LAS unsigned*)(lds + (bufoff) + ldsw + _i * 8192), 16, 0, 0); } while (0)
; #define PG8_LDA(dst, b, h) do { _Pragma("unroll") for (int m = 0; m < 4; ++m) _Pragma("unroll") for (int k = 0; k < 2; ++k) dst[m][k] = *(const PG8_LAS bf16x8*)(lds + PG8_SA(b, h) + aoff + m * 2048 + k * 1024); } while (0)
; #define PG8_LDB(dst, b, h) do { _Pragma("unroll") for (int n = 0; n < 2; ++n) _Pragma("unroll") for (int k = 0; k < 2; ++k) dst[n][k] = *(const PG8_LAS bf16x8*)(lds + PG8_SB(b, h) + boff + n * 2048 + k * 1024); } while (0)
; #define PG8_MMA(ai, bj, At, Bt) do { __builtin_amdgcn_s_setprio(1); _Pragma("unroll") for (int m = 0; m < 4; ++m) _Pragma("unroll") for (int n = 0; n < 2; ++n) _Pragma("unroll") for (int k = 0; k < 2; ++k) \
;         acc[ai][bj][m][n] = __builtin_amdgcn_mfma_f32_16x16x32_bf16(Bt[n][k], At[m][k], acc[ai][bj][m][n], 0, 0, 0); __builtin_amdgcn_s_setprio(0); } while (0)
; #define PG8_WAIT_V(n) asm volatile("s_waitcnt vmcnt(" #n ")" ::: "memory")
; #define PG8_WAIT_L(n) asm volatile("s_waitcnt lgkmcnt(" #n ")" ::: "memory")
; template <class Epi, class Sched, bool ALIGN_EPI = false, bool SP2 = false, bool AGM = false  >
; __device__ __forceinline__ void gemm_phase(PG8_LAS unsigned char* lds, const Gemm g, const Sched& S, const Epi& E) {
;     ...
;         const bool has_next = S.next(ui + 1, nxt);
;         const char* nA = has_next ? (const char*)g.A + (size_t)nxt.pm * tstepA : cA; const char* nB = has_next ? (const char*)g.Bt + (size_t)nxt.pn * tstep : cB;
;         for (int t = 0; t < nt; t += 2) {
;             const bool last = (t == nt - 2);
;             const char* a1 = cA + (size_t)(t + 1) * kstepA;
;             const char* a2 = last ? nA : cA + (size_t)(t + 2) * kstepA; const char* b2 = last ? nB : cB + (size_t)(t + 2) * kstep;
;             const char* a3 = a2 + kstepA; const char* b3 = b2 + kstep;
;             if (last && has_next) S.a_ready(nxt);
;             if constexpr (SP2) {
;             PG8_LDB(B0, 0, 0); PG8_LDB(B1, 0, 1); PG8_SCHED; PG8_LDA(At, 0, 0); PG8_STAGE(PG8_SA(1, 1), a1 + hstepA, voffA);
;             PG8_WAIT_V(8); PG8_WAIT_L(0); PG8_BAR; PG8_MMA(0, 0, At, B0); PG8_MMA(0, 1, At, B1); PG8_BAR; PG8_SCHED;
.LBB0_876:
	s_ashr_i32 s23, s22, 31
	s_lshl_b64 s[24:25], s[22:23], 19
	s_add_u32 s24, s46, s24
	s_addc_u32 s25, s47, s25
	s_and_b64 s[26:27], s[0:1], exec
	s_cselect_b32 s23, s25, s29
	s_cselect_b32 s64, s24, s28
	s_ashr_i32 s21, s20, 31
	s_lshl_b64 s[26:27], s[20:21], 19
	s_add_u32 s26, s10, s26
	s_addc_u32 s27, s11, s27
	s_and_b64 s[34:35], s[0:1], exec
	s_cselect_b32 s21, s27, s31
	s_cselect_b32 s65, s26, s30
	s_add_u32 s28, s28, 0x40080
	s_addc_u32 s29, s29, 0
	s_add_u32 s66, s30, 0x100
	s_addc_u32 s67, s31, 0
	s_mov_b32 s68, -2
	s_waitcnt lgkmcnt(0)
	ds_read_b128 v[148:151], v156
	ds_read_b128 v[164:167], v156 offset:1024
	ds_read_b128 v[168:171], v156 offset:2048
	ds_read_b128 v[172:175], v156 offset:3072
	ds_read_b128 v[176:179], v157
	ds_read_b128 v[180:183], v157 offset:1024
	ds_read_b128 v[184:187], v157 offset:2048
	ds_read_b128 v[188:191], v157 offset:3072
	s_add_u32 s30, s28, 0xfffc0080
	s_addc_u32 s31, s29, -1
	s_cmp_eq_u32 s68, 12
	s_cselect_b32 s35, s23, s31
	s_cselect_b32 s34, s64, s30
	s_cselect_b32 s31, s21, s67
	s_cselect_b32 s30, s65, s66
	v_lshl_add_u64 v[224:225], s[28:29], 0, v[140:141]
	s_add_i32 m0, s37, 0xc000
	ds_read_b128 v[192:195], v158
	ds_read_b128 v[196:199], v158 offset:1024
	ds_read_b128 v[200:203], v158 offset:2048
	ds_read_b128 v[204:207], v158 offset:3072
	ds_read_b128 v[208:211], v158 offset:4096
	ds_read_b128 v[212:215], v158 offset:5120
	ds_read_b128 v[216:219], v158 offset:6144
	ds_read_b128 v[220:223], v158 offset:7168
	global_load_lds_dwordx4 v[224:225], off
	v_lshl_add_u64 v[224:225], s[28:29], 0, v[142:143]
	s_add_i32 m0, s37, 0xe000
	s_nop 0
	global_load_lds_dwordx4 v[224:225], off
	s_waitcnt vmcnt(8)
	s_waitcnt lgkmcnt(0)
	s_barrier
	s_setprio 1
	s_waitcnt lgkmcnt(0)
	v_mfma_f32_16x16x32_bf16 v[126:129], v[148:151], v[192:195], 0
	v_mfma_f32_16x16x32_bf16 v[122:125], v[168:171], v[192:195], 0
	v_mfma_f32_16x16x32_bf16 v[110:113], v[148:151], v[200:203], 0
	v_mfma_f32_16x16x32_bf16 v[106:109], v[168:171], v[200:203], 0
	v_mfma_f32_16x16x32_bf16 v[94:97], v[148:151], v[208:211], 0
	v_mfma_f32_16x16x32_bf16 v[90:93], v[168:171], v[208:211], 0
	v_mfma_f32_16x16x32_bf16 v[78:81], v[148:151], v[216:219], 0
	v_mfma_f32_16x16x32_bf16 v[74:77], v[168:171], v[216:219], 0
	v_mfma_f32_16x16x32_bf16 v[126:129], v[164:167], v[196:199], v[126:129]
	v_mfma_f32_16x16x32_bf16 v[122:125], v[172:175], v[196:199], v[122:125]
	v_mfma_f32_16x16x32_bf16 v[110:113], v[164:167], v[204:207], v[110:113]
	v_mfma_f32_16x16x32_bf16 v[106:109], v[172:175], v[204:207], v[106:109]
	v_mfma_f32_16x16x32_bf16 v[94:97], v[164:167], v[212:215], v[94:97]
	v_mfma_f32_16x16x32_bf16 v[90:93], v[172:175], v[212:215], v[90:93]
	v_mfma_f32_16x16x32_bf16 v[78:81], v[164:167], v[220:223], v[78:81]
	v_mfma_f32_16x16x32_bf16 v[74:77], v[172:175], v[220:223], v[74:77]
	s_setprio 0
	s_setprio 1
	v_mfma_f32_16x16x32_bf16 v[118:121], v[176:179], v[192:195], 0
	v_mfma_f32_16x16x32_bf16 v[114:117], v[184:187], v[192:195], 0
	v_mfma_f32_16x16x32_bf16 v[102:105], v[176:179], v[200:203], 0
	v_mfma_f32_16x16x32_bf16 v[98:101], v[184:187], v[200:203], 0
	v_mfma_f32_16x16x32_bf16 v[86:89], v[176:179], v[208:211], 0
	v_mfma_f32_16x16x32_bf16 v[82:85], v[184:187], v[208:211], 0
	v_mfma_f32_16x16x32_bf16 v[70:73], v[176:179], v[216:219], 0
	v_mfma_f32_16x16x32_bf16 v[66:69], v[184:187], v[216:219], 0
	v_mfma_f32_16x16x32_bf16 v[118:121], v[180:183], v[196:199], v[118:121]
	v_mfma_f32_16x16x32_bf16 v[114:117], v[188:191], v[196:199], v[114:117]
	v_mfma_f32_16x16x32_bf16 v[102:105], v[180:183], v[204:207], v[102:105]
	v_mfma_f32_16x16x32_bf16 v[98:101], v[188:191], v[204:207], v[98:101]
	v_mfma_f32_16x16x32_bf16 v[86:89], v[180:183], v[212:215], v[86:89]
	v_mfma_f32_16x16x32_bf16 v[82:85], v[188:191], v[212:215], v[82:85]
	v_mfma_f32_16x16x32_bf16 v[70:73], v[180:183], v[220:223], v[70:73]
	v_mfma_f32_16x16x32_bf16 v[66:69], v[188:191], v[220:223], v[66:69]
	s_setprio 0
	s_barrier
	s_add_i32 s69, s53, s3
	v_lshl_add_u64 v[224:225], s[30:31], 0, v[134:135]
	s_mov_b32 m0, s69
	ds_read_b128 v[192:195], v158 offset:16384
	ds_read_b128 v[196:199], v158 offset:17408
	ds_read_b128 v[200:203], v158 offset:18432
	ds_read_b128 v[204:207], v158 offset:19456
	ds_read_b128 v[208:211], v158 offset:20480
	ds_read_b128 v[212:215], v158 offset:21504
	ds_read_b128 v[216:219], v158 offset:22528
	ds_read_b128 v[220:223], v158 offset:23552
	global_load_lds_dwordx4 v[224:225], off
	s_add_i32 m0, s69, 0x2000
	s_add_u32 s70, s30, 0x40000
	v_lshl_add_u64 v[226:227], s[30:31], 0, v[130:131]
	s_addc_u32 s71, s31, 0
	s_add_i32 s69, s54, s3
	global_load_lds_dwordx4 v[226:227], off
	v_lshl_add_u64 v[228:229], s[70:71], 0, v[134:135]
	s_mov_b32 m0, s69
	v_lshl_add_u64 v[230:231], s[34:35], 0, v[132:133]
	global_load_lds_dwordx4 v[228:229], off
	v_lshl_add_u64 v[228:229], s[70:71], 0, v[130:131]
	s_add_i32 m0, s69, 0x2000
	s_nop 0
	global_load_lds_dwordx4 v[228:229], off
	v_lshl_add_u64 v[228:229], s[34:35], 0, v[136:137]
	s_mov_b32 m0, s37
	s_nop 0
	global_load_lds_dwordx4 v[228:229], off
	s_mov_b32 m0, s38
	s_nop 0
	global_load_lds_dwordx4 v[230:231], off
	s_waitcnt vmcnt(8)
	s_waitcnt lgkmcnt(0)
	s_barrier
; #define PG8_STAGE(bufoff, gbase, voff) do { _Pragma("unroll") for (int _i = 0; _i < 2; ++_i) \
;         __builtin_amdgcn_global_load_lds((const unsigned*)((const char*)(gbase) + (voff)[_i]), (PG8_LAS unsigned*)(lds + (bufoff) + ldsw + _i * 8192), 16, 0, 0); } while (0)
; #define PG8_LDA(dst, b, h) do { _Pragma("unroll") for (int m = 0; m < 4; ++m) _Pragma("unroll") for (int k = 0; k < 2; ++k) dst[m][k] = *(const PG8_LAS bf16x8*)(lds + PG8_SA(b, h) + aoff + m * 2048 + k * 1024); } while (0)
; #define PG8_LDB(dst, b, h) do { _Pragma("unroll") for (int n = 0; n < 2; ++n) _Pragma("unroll") for (int k = 0; k < 2; ++k) dst[n][k] = *(const PG8_LAS bf16x8*)(lds + PG8_SB(b, h) + boff + n * 2048 + k * 1024); } while (0)
; #define PG8_MMA(ai, bj, At, Bt) do { __builtin_amdgcn_s_setprio(1); _Pragma("unroll") for (int m = 0; m < 4; ++m) _Pragma("unroll") for (int n = 0; n < 2; ++n) _Pragma("unroll") for (int k = 0; k < 2; ++k) \
;         acc[ai][bj][m][n] = __builtin_amdgcn_mfma_f32_16x16x32_bf16(Bt[n][k], At[m][k], acc[ai][bj][m][n], 0, 0, 0); __builtin_amdgcn_s_setprio(0); } while (0)
; #define PG8_WAIT_V(n) asm volatile("s_waitcnt vmcnt(" #n ")" ::: "memory")
; #define PG8_WAIT_L(n) asm volatile("s_waitcnt lgkmcnt(" #n ")" ::: "memory")
; #define PG8_BAR __builtin_amdgcn_s_barrier()
; #define PG8_SCHED __builtin_amdgcn_sched_barrier(0)
; template <class Epi, class Sched, bool ALIGN_EPI = false, bool SP2 = false, bool AGM = false  >
; __device__ __forceinline__ void gemm_phase(PG8_LAS unsigned char* lds, const Gemm g, const Sched& S, const Epi& E) {
;     ...
;             PG8_WAIT_V(8); PG8_WAIT_L(0); PG8_BAR; PG8_MMA(1, 0, At, B0); PG8_MMA(1, 1, At, B1); PG8_BAR; PG8_SCHED;
;             PG8_LDB(B0, 1, 0); PG8_LDB(B1, 1, 1); PG8_SCHED; PG8_LDA(At, 1, 0); PG8_STAGE(PG8_SA(0, 1), a2 + hstepA, voffA);
;             PG8_WAIT_V(8); PG8_WAIT_L(0); PG8_BAR; PG8_MMA(0, 0, At, B0); PG8_MMA(0, 1, At, B1); PG8_BAR; PG8_SCHED;
	s_setprio 1
	s_waitcnt lgkmcnt(0)
	v_mfma_f32_16x16x32_bf16 v[62:65], v[148:151], v[192:195], 0
	v_mfma_f32_16x16x32_bf16 v[58:61], v[168:171], v[192:195], 0
	v_mfma_f32_16x16x32_bf16 v[46:49], v[148:151], v[200:203], 0
	v_mfma_f32_16x16x32_bf16 v[42:45], v[168:171], v[200:203], 0
	v_mfma_f32_16x16x32_bf16 v[30:33], v[148:151], v[208:211], 0
	v_mfma_f32_16x16x32_bf16 v[26:29], v[168:171], v[208:211], 0
	v_mfma_f32_16x16x32_bf16 v[14:17], v[148:151], v[216:219], 0
	v_mfma_f32_16x16x32_bf16 v[10:13], v[168:171], v[216:219], 0
	v_mfma_f32_16x16x32_bf16 v[62:65], v[164:167], v[196:199], v[62:65]
	v_mfma_f32_16x16x32_bf16 v[58:61], v[172:175], v[196:199], v[58:61]
	v_mfma_f32_16x16x32_bf16 v[46:49], v[164:167], v[204:207], v[46:49]
	v_mfma_f32_16x16x32_bf16 v[42:45], v[172:175], v[204:207], v[42:45]
	v_mfma_f32_16x16x32_bf16 v[30:33], v[164:167], v[212:215], v[30:33]
	v_mfma_f32_16x16x32_bf16 v[26:29], v[172:175], v[212:215], v[26:29]
	v_mfma_f32_16x16x32_bf16 v[14:17], v[164:167], v[220:223], v[14:17]
	v_mfma_f32_16x16x32_bf16 v[10:13], v[172:175], v[220:223], v[10:13]
	s_setprio 0
	s_setprio 1
	v_mfma_f32_16x16x32_bf16 v[54:57], v[176:179], v[192:195], 0
	v_mfma_f32_16x16x32_bf16 v[50:53], v[184:187], v[192:195], 0
	v_mfma_f32_16x16x32_bf16 v[38:41], v[176:179], v[200:203], 0
	v_mfma_f32_16x16x32_bf16 v[34:37], v[184:187], v[200:203], 0
	v_mfma_f32_16x16x32_bf16 v[22:25], v[176:179], v[208:211], 0
	v_mfma_f32_16x16x32_bf16 v[18:21], v[184:187], v[208:211], 0
	v_mfma_f32_16x16x32_bf16 v[6:9], v[176:179], v[216:219], 0
	v_mfma_f32_16x16x32_bf16 v[2:5], v[184:187], v[216:219], 0
	v_mfma_f32_16x16x32_bf16 v[54:57], v[180:183], v[196:199], v[54:57]
	v_mfma_f32_16x16x32_bf16 v[50:53], v[188:191], v[196:199], v[50:53]
	v_mfma_f32_16x16x32_bf16 v[38:41], v[180:183], v[204:207], v[38:41]
	v_mfma_f32_16x16x32_bf16 v[34:37], v[188:191], v[204:207], v[34:37]
	v_mfma_f32_16x16x32_bf16 v[22:25], v[180:183], v[212:215], v[22:25]
	v_mfma_f32_16x16x32_bf16 v[18:21], v[188:191], v[212:215], v[18:21]
	v_mfma_f32_16x16x32_bf16 v[6:9], v[180:183], v[220:223], v[6:9]
	v_mfma_f32_16x16x32_bf16 v[2:5], v[188:191], v[220:223], v[2:5]
	s_setprio 0
	s_barrier
	s_add_i32 s69, 0, 0x18000
	s_add_i32 s70, 0, 0x1c000
	v_add_u32_e32 v172, s69, v155
	v_add_u32_e32 v188, s70, v155
	ds_read_b128 v[148:151], v172
	ds_read_b128 v[164:167], v172 offset:1024
	ds_read_b128 v[168:171], v172 offset:2048
	ds_read_b128 v[172:175], v172 offset:3072
	ds_read_b128 v[176:179], v188
	ds_read_b128 v[180:183], v188 offset:1024
	ds_read_b128 v[184:187], v188 offset:2048
	ds_read_b128 v[188:191], v188 offset:3072
	s_add_u32 s34, s34, 0x40000
	s_addc_u32 s35, s35, 0
	s_mov_b32 m0, s39
	v_lshl_add_u64 v[232:233], s[34:35], 0, v[136:137]
	ds_read_b128 v[192:195], v158 offset:32768
	ds_read_b128 v[196:199], v158 offset:33792
	ds_read_b128 v[200:203], v158 offset:34816
	ds_read_b128 v[204:207], v158 offset:35840
	ds_read_b128 v[208:211], v158 offset:36864
	ds_read_b128 v[212:215], v158 offset:37888
	ds_read_b128 v[216:219], v158 offset:38912
	ds_read_b128 v[220:223], v158 offset:39936
	global_load_lds_dwordx4 v[232:233], off
	v_lshl_add_u64 v[232:233], s[34:35], 0, v[132:133]
	s_mov_b32 m0, s40
	s_nop 0
	global_load_lds_dwordx4 v[232:233], off
	s_waitcnt vmcnt(8)
	s_waitcnt lgkmcnt(0)
	s_barrier
	s_setprio 1
	s_waitcnt lgkmcnt(0)
	v_mfma_f32_16x16x32_bf16 v[126:129], v[148:151], v[192:195], v[126:129]
	v_mfma_f32_16x16x32_bf16 v[122:125], v[168:171], v[192:195], v[122:125]
	v_mfma_f32_16x16x32_bf16 v[110:113], v[148:151], v[200:203], v[110:113]
	v_mfma_f32_16x16x32_bf16 v[106:109], v[168:171], v[200:203], v[106:109]
	v_mfma_f32_16x16x32_bf16 v[94:97], v[148:151], v[208:211], v[94:97]
	v_mfma_f32_16x16x32_bf16 v[90:93], v[168:171], v[208:211], v[90:93]
	v_mfma_f32_16x16x32_bf16 v[78:81], v[148:151], v[216:219], v[78:81]
	v_mfma_f32_16x16x32_bf16 v[74:77], v[168:171], v[216:219], v[74:77]
	v_mfma_f32_16x16x32_bf16 v[126:129], v[164:167], v[196:199], v[126:129]
	v_mfma_f32_16x16x32_bf16 v[122:125], v[172:175], v[196:199], v[122:125]
	v_mfma_f32_16x16x32_bf16 v[110:113], v[164:167], v[204:207], v[110:113]
	v_mfma_f32_16x16x32_bf16 v[106:109], v[172:175], v[204:207], v[106:109]
	v_mfma_f32_16x16x32_bf16 v[94:97], v[164:167], v[212:215], v[94:97]
	v_mfma_f32_16x16x32_bf16 v[90:93], v[172:175], v[212:215], v[90:93]
	v_mfma_f32_16x16x32_bf16 v[78:81], v[164:167], v[220:223], v[78:81]
	v_mfma_f32_16x16x32_bf16 v[74:77], v[172:175], v[220:223], v[74:77]
	s_setprio 0
	s_setprio 1
	v_mfma_f32_16x16x32_bf16 v[118:121], v[176:179], v[192:195], v[118:121]
	v_mfma_f32_16x16x32_bf16 v[114:117], v[184:187], v[192:195], v[114:117]
	v_mfma_f32_16x16x32_bf16 v[102:105], v[176:179], v[200:203], v[102:105]
	v_mfma_f32_16x16x32_bf16 v[98:101], v[184:187], v[200:203], v[98:101]
	v_mfma_f32_16x16x32_bf16 v[86:89], v[176:179], v[208:211], v[86:89]
	v_mfma_f32_16x16x32_bf16 v[82:85], v[184:187], v[208:211], v[82:85]
	v_mfma_f32_16x16x32_bf16 v[70:73], v[176:179], v[216:219], v[70:73]
	v_mfma_f32_16x16x32_bf16 v[66:69], v[184:187], v[216:219], v[66:69]
	v_mfma_f32_16x16x32_bf16 v[118:121], v[180:183], v[196:199], v[118:121]
	v_mfma_f32_16x16x32_bf16 v[114:117], v[188:191], v[196:199], v[114:117]
	v_mfma_f32_16x16x32_bf16 v[102:105], v[180:183], v[204:207], v[102:105]
	v_mfma_f32_16x16x32_bf16 v[98:101], v[188:191], v[204:207], v[98:101]
	v_mfma_f32_16x16x32_bf16 v[86:89], v[180:183], v[212:215], v[86:89]
	v_mfma_f32_16x16x32_bf16 v[82:85], v[188:191], v[212:215], v[82:85]
	v_mfma_f32_16x16x32_bf16 v[70:73], v[180:183], v[220:223], v[70:73]
	v_mfma_f32_16x16x32_bf16 v[66:69], v[188:191], v[220:223], v[66:69]
	s_setprio 0
	s_barrier
; #define PG8_STAGE(bufoff, gbase, voff) do { _Pragma("unroll") for (int _i = 0; _i < 2; ++_i) \
;         __builtin_amdgcn_global_load_lds((const unsigned*)((const char*)(gbase) + (voff)[_i]), (PG8_LAS unsigned*)(lds + (bufoff) + ldsw + _i * 8192), 16, 0, 0); } while (0)
; #define PG8_LDA(dst, b, h) do { _Pragma("unroll") for (int m = 0; m < 4; ++m) _Pragma("unroll") for (int k = 0; k < 2; ++k) dst[m][k] = *(const PG8_LAS bf16x8*)(lds + PG8_SA(b, h) + aoff + m * 2048 + k * 1024); } while (0)
; #define PG8_MMA(ai, bj, At, Bt) do { __builtin_amdgcn_s_setprio(1); _Pragma("unroll") for (int m = 0; m < 4; ++m) _Pragma("unroll") for (int n = 0; n < 2; ++n) _Pragma("unroll") for (int k = 0; k < 2; ++k) \
;         acc[ai][bj][m][n] = __builtin_amdgcn_mfma_f32_16x16x32_bf16(Bt[n][k], At[m][k], acc[ai][bj][m][n], 0, 0, 0); __builtin_amdgcn_s_setprio(0); } while (0)
; #define PG8_WAIT_V(n) asm volatile("s_waitcnt vmcnt(" #n ")" ::: "memory")
; #define PG8_WAIT_L(n) asm volatile("s_waitcnt lgkmcnt(" #n ")" ::: "memory")
; #define PG8_BAR __builtin_amdgcn_s_barrier()
; #define PG8_SCHED __builtin_amdgcn_sched_barrier(0)
; template <class Epi, class Sched, bool ALIGN_EPI = false, bool SP2 = false, bool AGM = false  >
; __device__ __forceinline__ void gemm_phase(PG8_LAS unsigned char* lds, const Gemm g, const Sched& S, const Epi& E) {
;     ...
;             PG8_LDA(At, 1, 1); PG8_STAGE(PG8_SB(1, 0), b3, voffB); PG8_STAGE(PG8_SB(1, 1), b3 + hstep, voffB); PG8_STAGE(PG8_SA(1, 0), a3, voffA);
;             PG8_WAIT_V(8); PG8_WAIT_L(0); PG8_BAR; PG8_MMA(1, 0, At, B0); PG8_MMA(1, 1, At, B1); PG8_BAR; PG8_SCHED;
	s_add_i32 s34, s69, s3
	v_lshl_add_u64 v[224:225], v[224:225], 0, s[16:17]
	s_mov_b32 m0, s34
	ds_read_b128 v[192:195], v158 offset:49152
	ds_read_b128 v[196:199], v158 offset:50176
	ds_read_b128 v[200:203], v158 offset:51200
	ds_read_b128 v[204:207], v158 offset:52224
	ds_read_b128 v[208:211], v158 offset:53248
	ds_read_b128 v[212:215], v158 offset:54272
	ds_read_b128 v[216:219], v158 offset:55296
	ds_read_b128 v[220:223], v158 offset:56320
	global_load_lds_dwordx4 v[224:225], off
	s_add_i32 m0, s34, 0x2000
	s_add_u32 s30, s30, 0x40080
	v_lshl_add_u64 v[224:225], v[226:227], 0, s[16:17]
	s_addc_u32 s31, s31, 0
	s_add_i32 s34, s70, s3
	global_load_lds_dwordx4 v[224:225], off
	v_lshl_add_u64 v[224:225], s[30:31], 0, v[134:135]
	s_mov_b32 m0, s34
	s_nop 0
	global_load_lds_dwordx4 v[224:225], off
	v_lshl_add_u64 v[224:225], s[30:31], 0, v[130:131]
	s_add_i32 m0, s34, 0x2000
	s_nop 0
	global_load_lds_dwordx4 v[224:225], off
	v_lshl_add_u64 v[224:225], v[228:229], 0, s[16:17]
	s_mov_b32 m0, s43
	s_nop 0
	global_load_lds_dwordx4 v[224:225], off
	v_lshl_add_u64 v[224:225], v[230:231], 0, s[16:17]
	s_mov_b32 m0, s44
	s_nop 0
	global_load_lds_dwordx4 v[224:225], off
	s_waitcnt vmcnt(8)
	s_waitcnt lgkmcnt(0)
	s_barrier
	s_setprio 1
	s_waitcnt lgkmcnt(0)
	v_mfma_f32_16x16x32_bf16 v[62:65], v[148:151], v[192:195], v[62:65]
	v_mfma_f32_16x16x32_bf16 v[58:61], v[168:171], v[192:195], v[58:61]
	v_mfma_f32_16x16x32_bf16 v[46:49], v[148:151], v[200:203], v[46:49]
	v_mfma_f32_16x16x32_bf16 v[42:45], v[168:171], v[200:203], v[42:45]
	v_mfma_f32_16x16x32_bf16 v[30:33], v[148:151], v[208:211], v[30:33]
	v_mfma_f32_16x16x32_bf16 v[26:29], v[168:171], v[208:211], v[26:29]
	v_mfma_f32_16x16x32_bf16 v[14:17], v[148:151], v[216:219], v[14:17]
	v_mfma_f32_16x16x32_bf16 v[10:13], v[168:171], v[216:219], v[10:13]
	v_mfma_f32_16x16x32_bf16 v[62:65], v[164:167], v[196:199], v[62:65]
	v_mfma_f32_16x16x32_bf16 v[58:61], v[172:175], v[196:199], v[58:61]
	v_mfma_f32_16x16x32_bf16 v[46:49], v[164:167], v[204:207], v[46:49]
	v_mfma_f32_16x16x32_bf16 v[42:45], v[172:175], v[204:207], v[42:45]
	v_mfma_f32_16x16x32_bf16 v[30:33], v[164:167], v[212:215], v[30:33]
	v_mfma_f32_16x16x32_bf16 v[26:29], v[172:175], v[212:215], v[26:29]
	v_mfma_f32_16x16x32_bf16 v[14:17], v[164:167], v[220:223], v[14:17]
	v_mfma_f32_16x16x32_bf16 v[10:13], v[172:175], v[220:223], v[10:13]
	s_setprio 0
	s_setprio 1
	v_mfma_f32_16x16x32_bf16 v[54:57], v[176:179], v[192:195], v[54:57]
	v_mfma_f32_16x16x32_bf16 v[50:53], v[184:187], v[192:195], v[50:53]
	v_mfma_f32_16x16x32_bf16 v[38:41], v[176:179], v[200:203], v[38:41]
	v_mfma_f32_16x16x32_bf16 v[34:37], v[184:187], v[200:203], v[34:37]
	v_mfma_f32_16x16x32_bf16 v[22:25], v[176:179], v[208:211], v[22:25]
	v_mfma_f32_16x16x32_bf16 v[18:21], v[184:187], v[208:211], v[18:21]
	v_mfma_f32_16x16x32_bf16 v[6:9], v[176:179], v[216:219], v[6:9]
	v_mfma_f32_16x16x32_bf16 v[2:5], v[184:187], v[216:219], v[2:5]
	v_mfma_f32_16x16x32_bf16 v[54:57], v[180:183], v[196:199], v[54:57]
	v_mfma_f32_16x16x32_bf16 v[50:53], v[188:191], v[196:199], v[50:53]
	v_mfma_f32_16x16x32_bf16 v[38:41], v[180:183], v[204:207], v[38:41]
	v_mfma_f32_16x16x32_bf16 v[34:37], v[188:191], v[204:207], v[34:37]
	v_mfma_f32_16x16x32_bf16 v[22:25], v[180:183], v[212:215], v[22:25]
	v_mfma_f32_16x16x32_bf16 v[18:21], v[188:191], v[212:215], v[18:21]
	v_mfma_f32_16x16x32_bf16 v[6:9], v[180:183], v[220:223], v[6:9]
	v_mfma_f32_16x16x32_bf16 v[2:5], v[188:191], v[220:223], v[2:5]
	s_setprio 0
	s_barrier
	s_add_i32 s68, s68, 2
	s_add_u32 s28, s28, 0x100
	s_addc_u32 s29, s29, 0
	s_add_u32 s66, s66, 0x100
	s_addc_u32 s67, s67, 0
	s_cmp_gt_u32 s68, 13
	s_cbranch_scc1 .Lpeel_done_p6

; template <class Epi, class Sched, bool ALIGN_EPI = false, bool SP2 = false, bool AGM = false  >
; __device__ __forceinline__ void gemm_phase(PG8_LAS unsigned char* lds, const Gemm g, const Sched& S, const Epi& E) {
;     ...
;     Unit cur, nxt; int ui = 0;
;     if (!S.next(0, cur)) return;
;     f32x4 acc[2][2][4][2];
; #pragma unroll
;     for (int a = 0; a < 2; ++a)
; #pragma unroll
;         for (int b = 0; b < 2; ++b)
; #pragma unroll
;             for (int m = 0; m < 4; ++m)
; #pragma unroll
;                 for (int n = 0; n < 2; ++n) acc[a][b][m][n] = (f32x4){0.f, 0.f, 0.f, 0.f};
;     ...
;         const bool has_next = S.next(ui + 1, nxt);
;         const char* nA = has_next ? (const char*)g.A + (size_t)nxt.pm * tstepA : cA; const char* nB = has_next ? (const char*)g.Bt + (size_t)nxt.pn * tstep : cB;
.LBB0_1067:
	s_add_u32 s30, s30, 0xb0080
	s_addc_u32 s31, s31, 0
	s_add_u32 s5, s34, 0x100
	v_mov_b32_e32 v2, 0
	s_addc_u32 s33, s35, 0
	s_mov_b32 s65, -2
	v_mov_b32_e32 v3, v2
	v_mov_b32_e32 v4, v2
	v_mov_b32_e32 v5, v2
	v_mov_b32_e32 v6, v2
	v_mov_b32_e32 v7, v2
	v_mov_b32_e32 v8, v2
	v_mov_b32_e32 v9, v2
	v_mov_b32_e32 v18, v2
	v_mov_b32_e32 v19, v2
	v_mov_b32_e32 v20, v2
	v_mov_b32_e32 v21, v2
	v_mov_b32_e32 v22, v2
	v_mov_b32_e32 v23, v2
	v_mov_b32_e32 v24, v2
	v_mov_b32_e32 v25, v2
	v_mov_b32_e32 v34, v2
	v_mov_b32_e32 v35, v2
	v_mov_b32_e32 v36, v2
	v_mov_b32_e32 v37, v2
	v_mov_b32_e32 v38, v2
	v_mov_b32_e32 v39, v2
	v_mov_b32_e32 v40, v2
	v_mov_b32_e32 v41, v2
	v_mov_b32_e32 v50, v2
	v_mov_b32_e32 v51, v2
	v_mov_b32_e32 v52, v2
	v_mov_b32_e32 v53, v2
	v_mov_b32_e32 v54, v2
	v_mov_b32_e32 v55, v2
	v_mov_b32_e32 v56, v2
	v_mov_b32_e32 v57, v2
	v_mov_b32_e32 v10, v2
	v_mov_b32_e32 v11, v2
	v_mov_b32_e32 v12, v2
	v_mov_b32_e32 v13, v2
	v_mov_b32_e32 v14, v2
	v_mov_b32_e32 v15, v2
	v_mov_b32_e32 v16, v2
	v_mov_b32_e32 v17, v2
	v_mov_b32_e32 v26, v2
	v_mov_b32_e32 v27, v2
	s_waitcnt lgkmcnt(0)
	v_mov_b32_e32 v28, v2
	v_mov_b32_e32 v29, v2
	v_mov_b32_e32 v30, v2
	v_mov_b32_e32 v31, v2
	v_mov_b32_e32 v32, v2
	v_mov_b32_e32 v33, v2
	v_mov_b32_e32 v42, v2
	v_mov_b32_e32 v43, v2
	v_mov_b32_e32 v44, v2
	v_mov_b32_e32 v45, v2
	v_mov_b32_e32 v46, v2
	v_mov_b32_e32 v47, v2
	v_mov_b32_e32 v48, v2
	v_mov_b32_e32 v49, v2
	v_mov_b32_e32 v58, v2
	v_mov_b32_e32 v59, v2
	v_mov_b32_e32 v60, v2
	v_mov_b32_e32 v61, v2
	v_mov_b32_e32 v62, v2
	v_mov_b32_e32 v63, v2
	v_mov_b32_e32 v64, v2
	v_mov_b32_e32 v65, v2
	v_mov_b32_e32 v66, v2
	v_mov_b32_e32 v67, v2
	v_mov_b32_e32 v68, v2
	v_mov_b32_e32 v69, v2
	v_mov_b32_e32 v70, v2
	v_mov_b32_e32 v71, v2
	v_mov_b32_e32 v72, v2
	v_mov_b32_e32 v73, v2
	v_mov_b32_e32 v82, v2
	v_mov_b32_e32 v83, v2
	v_mov_b32_e32 v84, v2
	v_mov_b32_e32 v85, v2
	v_mov_b32_e32 v86, v2
	v_mov_b32_e32 v87, v2
	v_mov_b32_e32 v88, v2
	v_mov_b32_e32 v89, v2
	v_mov_b32_e32 v98, v2
	v_mov_b32_e32 v99, v2
	v_mov_b32_e32 v100, v2
	v_mov_b32_e32 v101, v2
	v_mov_b32_e32 v102, v2
	v_mov_b32_e32 v103, v2
	v_mov_b32_e32 v104, v2
	v_mov_b32_e32 v105, v2
	v_mov_b32_e32 v114, v2
	v_mov_b32_e32 v115, v2
	v_mov_b32_e32 v116, v2
	v_mov_b32_e32 v117, v2
	v_mov_b32_e32 v118, v2
	v_mov_b32_e32 v119, v2
	v_mov_b32_e32 v120, v2
	v_mov_b32_e32 v121, v2
	v_mov_b32_e32 v74, v2
	v_mov_b32_e32 v75, v2
	v_mov_b32_e32 v76, v2
	v_mov_b32_e32 v77, v2
	v_mov_b32_e32 v78, v2
	v_mov_b32_e32 v79, v2
	v_mov_b32_e32 v80, v2
	v_mov_b32_e32 v81, v2
	v_mov_b32_e32 v90, v2
	v_mov_b32_e32 v91, v2
	v_mov_b32_e32 v92, v2
	v_mov_b32_e32 v93, v2
	v_mov_b32_e32 v94, v2
	v_mov_b32_e32 v95, v2
	v_mov_b32_e32 v96, v2
	v_mov_b32_e32 v97, v2
	v_mov_b32_e32 v106, v2
	v_mov_b32_e32 v107, v2
	v_mov_b32_e32 v108, v2
	v_mov_b32_e32 v109, v2
	v_mov_b32_e32 v110, v2
	v_mov_b32_e32 v111, v2
	v_mov_b32_e32 v112, v2
	v_mov_b32_e32 v113, v2
	v_mov_b32_e32 v122, v2
	v_mov_b32_e32 v123, v2
	v_mov_b32_e32 v124, v2
	v_mov_b32_e32 v125, v2
	v_mov_b32_e32 v126, v2
	v_mov_b32_e32 v127, v2
	v_mov_b32_e32 v128, v2
	v_mov_b32_e32 v129, v2
